# up-projection row scales: 16-row wave reductions batched 8 rows per LDS round trip (same op order per row)
# speedup vs baseline: 1.0650x; 1.0064x over previous
; __device__ __forceinline__ float bf2f(unsigned short b) { return __uint_as_float(((unsigned)b) << 16); }
; template <int M> __device__ __forceinline__ float shx(float v) { return __builtin_bit_cast(float, __builtin_amdgcn_ds_swizzle(__builtin_bit_cast(int, v), (M << 10) | 0x1f)); }
; __device__ __forceinline__ float sum32(float v) { return v + xhalf(v); }
; __device__ __forceinline__ float wave_sum(float v) {
;   v += shx<16>(v); v += shx<8>(v); v += shx<4>(v); v += shx<2>(v); v += shx<1>(v); return sum32(v);
; }
; __device__ __forceinline__ void up_phase(const bf16_t* cqkv, const bf16_t* wqb, const bf16_t* wkvb, EpiUp& epi) {
;     ...
;     for (int r0 = 0; r0 < 32; r0 += 16) {
;       u32x2 wv[16];
; #pragma unroll
;       for (int rr = 0; rr < 16; ++rr) { if (isq) wv[rr] = *(const u32x2*)(rp + (size_t)(r0 + rr) * 512); else { wv[rr].x = *(const unsigned*)(rp + (size_t)(r0 + rr) * 512); wv[rr].y = 0u; } }
; #pragma unroll
;       for (int rr = 0; rr < 16; ++rr) {
;         const float a = bf2f(wv[rr].x & 0xffff), b = bf2f(wv[rr].x >> 16), c = bf2f(wv[rr].y & 0xffff), d = bf2f(wv[rr].y >> 16);
;         const float ss = wave_sum(a * a + b * b + c * c + d * d);
;         if (lane == 0) rsb[wid * 32 + r0 + rr] = rsqrtf(ss * (isq ? 1.0f / 256.0f : 1.0f / 128.0f) + 1e-6f);
;       }
.LBB0_908:
	s_waitcnt vmcnt(0)
	v_lshlrev_b32_e32 v36, 16, v32
	v_and_b32_e32 v32, 0xffff0000, v32
	v_mul_f32_e32 v32, v32, v32
	v_lshlrev_b32_e32 v37, 16, v33
	v_fmac_f32_e32 v32, v36, v36
	v_and_b32_e32 v33, 0xffff0000, v33
	v_fmac_f32_e32 v32, v37, v37
	v_fmac_f32_e32 v32, v33, v33
	v_lshlrev_b32_e32 v36, 16, v34
	v_and_b32_e32 v34, 0xffff0000, v34
	v_mul_f32_e32 v34, v34, v34
	v_lshlrev_b32_e32 v37, 16, v35
	v_fmac_f32_e32 v34, v36, v36
	v_and_b32_e32 v35, 0xffff0000, v35
	v_fmac_f32_e32 v34, v37, v37
	v_fmac_f32_e32 v34, v35, v35
	v_lshlrev_b32_e32 v36, 16, v30
	v_and_b32_e32 v30, 0xffff0000, v30
	v_mul_f32_e32 v30, v30, v30
	v_lshlrev_b32_e32 v37, 16, v31
	v_fmac_f32_e32 v30, v36, v36
	v_and_b32_e32 v31, 0xffff0000, v31
	v_fmac_f32_e32 v30, v37, v37
	v_fmac_f32_e32 v30, v31, v31
	v_lshlrev_b32_e32 v36, 16, v28
	v_and_b32_e32 v28, 0xffff0000, v28
	v_mul_f32_e32 v28, v28, v28
	v_lshlrev_b32_e32 v37, 16, v29
	v_fmac_f32_e32 v28, v36, v36
	v_and_b32_e32 v29, 0xffff0000, v29
	v_fmac_f32_e32 v28, v37, v37
	v_fmac_f32_e32 v28, v29, v29
	v_lshlrev_b32_e32 v36, 16, v26
	v_and_b32_e32 v26, 0xffff0000, v26
	v_mul_f32_e32 v26, v26, v26
	v_lshlrev_b32_e32 v37, 16, v27
	v_fmac_f32_e32 v26, v36, v36
	v_and_b32_e32 v27, 0xffff0000, v27
	v_fmac_f32_e32 v26, v37, v37
	v_fmac_f32_e32 v26, v27, v27
	v_lshlrev_b32_e32 v36, 16, v24
	v_and_b32_e32 v24, 0xffff0000, v24
	v_mul_f32_e32 v24, v24, v24
	v_lshlrev_b32_e32 v37, 16, v25
	v_fmac_f32_e32 v24, v36, v36
	v_and_b32_e32 v25, 0xffff0000, v25
	v_fmac_f32_e32 v24, v37, v37
	v_fmac_f32_e32 v24, v25, v25
	v_lshlrev_b32_e32 v36, 16, v22
	v_and_b32_e32 v22, 0xffff0000, v22
	v_mul_f32_e32 v22, v22, v22
	v_lshlrev_b32_e32 v37, 16, v23
	v_fmac_f32_e32 v22, v36, v36
	v_and_b32_e32 v23, 0xffff0000, v23
	v_fmac_f32_e32 v22, v37, v37
	v_fmac_f32_e32 v22, v23, v23
	v_lshlrev_b32_e32 v36, 16, v20
	v_and_b32_e32 v20, 0xffff0000, v20
	v_mul_f32_e32 v20, v20, v20
	v_lshlrev_b32_e32 v37, 16, v21
	v_fmac_f32_e32 v20, v36, v36
	v_and_b32_e32 v21, 0xffff0000, v21
	v_fmac_f32_e32 v20, v37, v37
	v_fmac_f32_e32 v20, v21, v21
	v_lshlrev_b32_e32 v36, 16, v18
	v_and_b32_e32 v18, 0xffff0000, v18
	v_mul_f32_e32 v18, v18, v18
	v_lshlrev_b32_e32 v37, 16, v19
	v_fmac_f32_e32 v18, v36, v36
	v_and_b32_e32 v19, 0xffff0000, v19
	v_fmac_f32_e32 v18, v37, v37
	v_fmac_f32_e32 v18, v19, v19
	v_lshlrev_b32_e32 v36, 16, v16
	v_and_b32_e32 v16, 0xffff0000, v16
	v_mul_f32_e32 v16, v16, v16
	v_lshlrev_b32_e32 v37, 16, v17
	v_fmac_f32_e32 v16, v36, v36
	v_and_b32_e32 v17, 0xffff0000, v17
	v_fmac_f32_e32 v16, v37, v37
	v_fmac_f32_e32 v16, v17, v17
	v_lshlrev_b32_e32 v36, 16, v14
	v_and_b32_e32 v14, 0xffff0000, v14
	v_mul_f32_e32 v14, v14, v14
	v_lshlrev_b32_e32 v37, 16, v15
	v_fmac_f32_e32 v14, v36, v36
	v_and_b32_e32 v15, 0xffff0000, v15
	v_fmac_f32_e32 v14, v37, v37
	v_fmac_f32_e32 v14, v15, v15
	v_lshlrev_b32_e32 v36, 16, v12
	v_and_b32_e32 v12, 0xffff0000, v12
	v_mul_f32_e32 v12, v12, v12
	v_lshlrev_b32_e32 v37, 16, v13
	v_fmac_f32_e32 v12, v36, v36
	v_and_b32_e32 v13, 0xffff0000, v13
	v_fmac_f32_e32 v12, v37, v37
	v_fmac_f32_e32 v12, v13, v13
	v_lshlrev_b32_e32 v36, 16, v10
	v_and_b32_e32 v10, 0xffff0000, v10
	v_mul_f32_e32 v10, v10, v10
	v_lshlrev_b32_e32 v37, 16, v11
	v_fmac_f32_e32 v10, v36, v36
	v_and_b32_e32 v11, 0xffff0000, v11
	v_fmac_f32_e32 v10, v37, v37
	v_fmac_f32_e32 v10, v11, v11
	v_lshlrev_b32_e32 v36, 16, v8
	v_and_b32_e32 v8, 0xffff0000, v8
	v_mul_f32_e32 v8, v8, v8
	v_lshlrev_b32_e32 v37, 16, v9
	v_fmac_f32_e32 v8, v36, v36
	v_and_b32_e32 v9, 0xffff0000, v9
	v_fmac_f32_e32 v8, v37, v37
	v_fmac_f32_e32 v8, v9, v9
	v_lshlrev_b32_e32 v36, 16, v6
	v_and_b32_e32 v6, 0xffff0000, v6
	v_mul_f32_e32 v6, v6, v6
	v_lshlrev_b32_e32 v37, 16, v7
	v_fmac_f32_e32 v6, v36, v36
	v_and_b32_e32 v7, 0xffff0000, v7
	v_fmac_f32_e32 v6, v37, v37
	v_fmac_f32_e32 v6, v7, v7
	v_lshlrev_b32_e32 v36, 16, v4
	v_and_b32_e32 v4, 0xffff0000, v4
	v_mul_f32_e32 v4, v4, v4
	v_lshlrev_b32_e32 v37, 16, v5
	v_fmac_f32_e32 v4, v36, v36
	v_and_b32_e32 v5, 0xffff0000, v5
	v_fmac_f32_e32 v4, v37, v37
	v_fmac_f32_e32 v4, v5, v5
	v_lshlrev_b32_e32 v37, 2, v210
	v_xor_b32_e32 v37, 0x80, v37
	ds_swizzle_b32 v33, v32 offset:swizzle(SWAP,16)
	ds_swizzle_b32 v35, v34 offset:swizzle(SWAP,16)
	ds_swizzle_b32 v31, v30 offset:swizzle(SWAP,16)
	ds_swizzle_b32 v29, v28 offset:swizzle(SWAP,16)
	ds_swizzle_b32 v27, v26 offset:swizzle(SWAP,16)
	ds_swizzle_b32 v25, v24 offset:swizzle(SWAP,16)
	ds_swizzle_b32 v23, v22 offset:swizzle(SWAP,16)
	ds_swizzle_b32 v21, v20 offset:swizzle(SWAP,16)
	s_waitcnt lgkmcnt(0)
	v_add_f32_e32 v32, v32, v33
	v_add_f32_e32 v34, v34, v35
	v_add_f32_e32 v30, v30, v31
	v_add_f32_e32 v28, v28, v29
	v_add_f32_e32 v26, v26, v27
	v_add_f32_e32 v24, v24, v25
	v_add_f32_e32 v22, v22, v23
	v_add_f32_e32 v20, v20, v21
	ds_swizzle_b32 v33, v32 offset:swizzle(SWAP,8)
	ds_swizzle_b32 v35, v34 offset:swizzle(SWAP,8)
	ds_swizzle_b32 v31, v30 offset:swizzle(SWAP,8)
	ds_swizzle_b32 v29, v28 offset:swizzle(SWAP,8)
	ds_swizzle_b32 v27, v26 offset:swizzle(SWAP,8)
	ds_swizzle_b32 v25, v24 offset:swizzle(SWAP,8)
	ds_swizzle_b32 v23, v22 offset:swizzle(SWAP,8)
	ds_swizzle_b32 v21, v20 offset:swizzle(SWAP,8)
	s_waitcnt lgkmcnt(0)
	v_add_f32_e32 v32, v32, v33
	v_add_f32_e32 v34, v34, v35
	v_add_f32_e32 v30, v30, v31
	v_add_f32_e32 v28, v28, v29
	v_add_f32_e32 v26, v26, v27
	v_add_f32_e32 v24, v24, v25
	v_add_f32_e32 v22, v22, v23
	v_add_f32_e32 v20, v20, v21
	ds_swizzle_b32 v33, v32 offset:swizzle(SWAP,4)
	ds_swizzle_b32 v35, v34 offset:swizzle(SWAP,4)
	ds_swizzle_b32 v31, v30 offset:swizzle(SWAP,4)
	ds_swizzle_b32 v29, v28 offset:swizzle(SWAP,4)
	ds_swizzle_b32 v27, v26 offset:swizzle(SWAP,4)
	ds_swizzle_b32 v25, v24 offset:swizzle(SWAP,4)
	ds_swizzle_b32 v23, v22 offset:swizzle(SWAP,4)
	ds_swizzle_b32 v21, v20 offset:swizzle(SWAP,4)
	s_waitcnt lgkmcnt(0)
; __device__ __forceinline__ float bf2f(unsigned short b) { return __uint_as_float(((unsigned)b) << 16); }
; template <int M> __device__ __forceinline__ float shx(float v) { return __builtin_bit_cast(float, __builtin_amdgcn_ds_swizzle(__builtin_bit_cast(int, v), (M << 10) | 0x1f)); }
; __device__ __forceinline__ float sum32(float v) { return v + xhalf(v); }
; __device__ __forceinline__ float wave_sum(float v) {
;   v += shx<16>(v); v += shx<8>(v); v += shx<4>(v); v += shx<2>(v); v += shx<1>(v); return sum32(v);
; }
; __device__ __forceinline__ void up_phase(const bf16_t* cqkv, const bf16_t* wqb, const bf16_t* wkvb, EpiUp& epi) {
;     ...
;     for (int r0 = 0; r0 < 32; r0 += 16) {
;       u32x2 wv[16];
; #pragma unroll
;       for (int rr = 0; rr < 16; ++rr) { if (isq) wv[rr] = *(const u32x2*)(rp + (size_t)(r0 + rr) * 512); else { wv[rr].x = *(const unsigned*)(rp + (size_t)(r0 + rr) * 512); wv[rr].y = 0u; } }
; #pragma unroll
;       for (int rr = 0; rr < 16; ++rr) {
;         const float a = bf2f(wv[rr].x & 0xffff), b = bf2f(wv[rr].x >> 16), c = bf2f(wv[rr].y & 0xffff), d = bf2f(wv[rr].y >> 16);
;         const float ss = wave_sum(a * a + b * b + c * c + d * d);
;         if (lane == 0) rsb[wid * 32 + r0 + rr] = rsqrtf(ss * (isq ? 1.0f / 256.0f : 1.0f / 128.0f) + 1e-6f);
;       }
	v_add_f32_e32 v32, v32, v33
	v_add_f32_e32 v34, v34, v35
	v_add_f32_e32 v30, v30, v31
	v_add_f32_e32 v28, v28, v29
	v_add_f32_e32 v26, v26, v27
	v_add_f32_e32 v24, v24, v25
	v_add_f32_e32 v22, v22, v23
	v_add_f32_e32 v20, v20, v21
	ds_swizzle_b32 v33, v32 offset:swizzle(SWAP,2)
	ds_swizzle_b32 v35, v34 offset:swizzle(SWAP,2)
	ds_swizzle_b32 v31, v30 offset:swizzle(SWAP,2)
	ds_swizzle_b32 v29, v28 offset:swizzle(SWAP,2)
	ds_swizzle_b32 v27, v26 offset:swizzle(SWAP,2)
	ds_swizzle_b32 v25, v24 offset:swizzle(SWAP,2)
	ds_swizzle_b32 v23, v22 offset:swizzle(SWAP,2)
	ds_swizzle_b32 v21, v20 offset:swizzle(SWAP,2)
	s_waitcnt lgkmcnt(0)
	v_add_f32_e32 v32, v32, v33
	v_add_f32_e32 v34, v34, v35
	v_add_f32_e32 v30, v30, v31
	v_add_f32_e32 v28, v28, v29
	v_add_f32_e32 v26, v26, v27
	v_add_f32_e32 v24, v24, v25
	v_add_f32_e32 v22, v22, v23
	v_add_f32_e32 v20, v20, v21
	ds_swizzle_b32 v33, v32 offset:swizzle(SWAP,1)
	ds_swizzle_b32 v35, v34 offset:swizzle(SWAP,1)
	ds_swizzle_b32 v31, v30 offset:swizzle(SWAP,1)
	ds_swizzle_b32 v29, v28 offset:swizzle(SWAP,1)
	ds_swizzle_b32 v27, v26 offset:swizzle(SWAP,1)
	ds_swizzle_b32 v25, v24 offset:swizzle(SWAP,1)
	ds_swizzle_b32 v23, v22 offset:swizzle(SWAP,1)
	ds_swizzle_b32 v21, v20 offset:swizzle(SWAP,1)
	s_waitcnt lgkmcnt(0)
	v_add_f32_e32 v32, v32, v33
	v_add_f32_e32 v34, v34, v35
	v_add_f32_e32 v30, v30, v31
	v_add_f32_e32 v28, v28, v29
	v_add_f32_e32 v26, v26, v27
	v_add_f32_e32 v24, v24, v25
	v_add_f32_e32 v22, v22, v23
	v_add_f32_e32 v20, v20, v21
	ds_bpermute_b32 v33, v37, v32
	ds_bpermute_b32 v35, v37, v34
	ds_bpermute_b32 v31, v37, v30
	ds_bpermute_b32 v29, v37, v28
	ds_bpermute_b32 v27, v37, v26
	ds_bpermute_b32 v25, v37, v24
	ds_bpermute_b32 v23, v37, v22
	ds_bpermute_b32 v21, v37, v20
	s_waitcnt lgkmcnt(0)
	v_add_f32_e32 v32, v32, v33
	v_add_f32_e32 v34, v34, v35
	v_add_f32_e32 v30, v30, v31
	v_add_f32_e32 v28, v28, v29
	v_add_f32_e32 v26, v26, v27
	v_add_f32_e32 v24, v24, v25
	v_add_f32_e32 v22, v22, v23
	v_add_f32_e32 v20, v20, v21
	ds_swizzle_b32 v19, v18 offset:swizzle(SWAP,16)
	ds_swizzle_b32 v17, v16 offset:swizzle(SWAP,16)
	ds_swizzle_b32 v15, v14 offset:swizzle(SWAP,16)
	ds_swizzle_b32 v13, v12 offset:swizzle(SWAP,16)
	ds_swizzle_b32 v11, v10 offset:swizzle(SWAP,16)
	ds_swizzle_b32 v9, v8 offset:swizzle(SWAP,16)
	ds_swizzle_b32 v7, v6 offset:swizzle(SWAP,16)
	ds_swizzle_b32 v5, v4 offset:swizzle(SWAP,16)
	s_waitcnt lgkmcnt(0)
	v_add_f32_e32 v18, v18, v19
	v_add_f32_e32 v16, v16, v17
	v_add_f32_e32 v14, v14, v15
	v_add_f32_e32 v12, v12, v13
	v_add_f32_e32 v10, v10, v11
	v_add_f32_e32 v8, v8, v9
	v_add_f32_e32 v6, v6, v7
	v_add_f32_e32 v4, v4, v5
	ds_swizzle_b32 v19, v18 offset:swizzle(SWAP,8)
	ds_swizzle_b32 v17, v16 offset:swizzle(SWAP,8)
	ds_swizzle_b32 v15, v14 offset:swizzle(SWAP,8)
	ds_swizzle_b32 v13, v12 offset:swizzle(SWAP,8)
	ds_swizzle_b32 v11, v10 offset:swizzle(SWAP,8)
	ds_swizzle_b32 v9, v8 offset:swizzle(SWAP,8)
	ds_swizzle_b32 v7, v6 offset:swizzle(SWAP,8)
	ds_swizzle_b32 v5, v4 offset:swizzle(SWAP,8)
	s_waitcnt lgkmcnt(0)
	v_add_f32_e32 v18, v18, v19
	v_add_f32_e32 v16, v16, v17
	v_add_f32_e32 v14, v14, v15
	v_add_f32_e32 v12, v12, v13
	v_add_f32_e32 v10, v10, v11
	v_add_f32_e32 v8, v8, v9
	v_add_f32_e32 v6, v6, v7
	v_add_f32_e32 v4, v4, v5
	ds_swizzle_b32 v19, v18 offset:swizzle(SWAP,4)
	ds_swizzle_b32 v17, v16 offset:swizzle(SWAP,4)
	ds_swizzle_b32 v15, v14 offset:swizzle(SWAP,4)
	ds_swizzle_b32 v13, v12 offset:swizzle(SWAP,4)
	ds_swizzle_b32 v11, v10 offset:swizzle(SWAP,4)
	ds_swizzle_b32 v9, v8 offset:swizzle(SWAP,4)
	ds_swizzle_b32 v7, v6 offset:swizzle(SWAP,4)
	ds_swizzle_b32 v5, v4 offset:swizzle(SWAP,4)
	s_waitcnt lgkmcnt(0)
	v_add_f32_e32 v18, v18, v19
	v_add_f32_e32 v16, v16, v17
	v_add_f32_e32 v14, v14, v15
	v_add_f32_e32 v12, v12, v13
	v_add_f32_e32 v10, v10, v11
	v_add_f32_e32 v8, v8, v9
	v_add_f32_e32 v6, v6, v7
	v_add_f32_e32 v4, v4, v5
	ds_swizzle_b32 v19, v18 offset:swizzle(SWAP,2)
	ds_swizzle_b32 v17, v16 offset:swizzle(SWAP,2)
	ds_swizzle_b32 v15, v14 offset:swizzle(SWAP,2)
	ds_swizzle_b32 v13, v12 offset:swizzle(SWAP,2)
	ds_swizzle_b32 v11, v10 offset:swizzle(SWAP,2)
	ds_swizzle_b32 v9, v8 offset:swizzle(SWAP,2)
	ds_swizzle_b32 v7, v6 offset:swizzle(SWAP,2)
	ds_swizzle_b32 v5, v4 offset:swizzle(SWAP,2)
	s_waitcnt lgkmcnt(0)
	v_add_f32_e32 v18, v18, v19
	v_add_f32_e32 v16, v16, v17
	v_add_f32_e32 v14, v14, v15
	v_add_f32_e32 v12, v12, v13
	v_add_f32_e32 v10, v10, v11
	v_add_f32_e32 v8, v8, v9
	v_add_f32_e32 v6, v6, v7
	v_add_f32_e32 v4, v4, v5
	ds_swizzle_b32 v19, v18 offset:swizzle(SWAP,1)
	ds_swizzle_b32 v17, v16 offset:swizzle(SWAP,1)
	ds_swizzle_b32 v15, v14 offset:swizzle(SWAP,1)
	ds_swizzle_b32 v13, v12 offset:swizzle(SWAP,1)
	ds_swizzle_b32 v11, v10 offset:swizzle(SWAP,1)
	ds_swizzle_b32 v9, v8 offset:swizzle(SWAP,1)
	ds_swizzle_b32 v7, v6 offset:swizzle(SWAP,1)
	ds_swizzle_b32 v5, v4 offset:swizzle(SWAP,1)
	s_waitcnt lgkmcnt(0)
	v_add_f32_e32 v18, v18, v19
	v_add_f32_e32 v16, v16, v17
	v_add_f32_e32 v14, v14, v15
	v_add_f32_e32 v12, v12, v13
	v_add_f32_e32 v10, v10, v11
	v_add_f32_e32 v8, v8, v9
	v_add_f32_e32 v6, v6, v7
	v_add_f32_e32 v4, v4, v5
	ds_bpermute_b32 v19, v37, v18
	ds_bpermute_b32 v17, v37, v16
	ds_bpermute_b32 v15, v37, v14
	ds_bpermute_b32 v13, v37, v12
	ds_bpermute_b32 v11, v37, v10
	ds_bpermute_b32 v9, v37, v8
	ds_bpermute_b32 v7, v37, v6
	ds_bpermute_b32 v5, v37, v4
	s_waitcnt lgkmcnt(0)
	v_add_f32_e32 v18, v18, v19
	v_add_f32_e32 v16, v16, v17
	v_add_f32_e32 v14, v14, v15
	v_add_f32_e32 v12, v12, v13
	v_add_f32_e32 v10, v10, v11
	v_add_f32_e32 v8, v8, v9
	v_add_f32_e32 v6, v6, v7
	v_add_f32_e32 v4, v4, v5
	v_lshl_add_u32 v36, s0, 2, v143
	s_and_saveexec_b64 s[4:5], s[2:3]
	s_cbranch_execz .LBB0_843
; __device__ __forceinline__ float bf2f(unsigned short b) { return __uint_as_float(((unsigned)b) << 16); }
; __device__ __forceinline__ void up_phase(const bf16_t* cqkv, const bf16_t* wqb, const bf16_t* wkvb, EpiUp& epi) {
;     ...
;     for (int r0 = 0; r0 < 32; r0 += 16) {
;       u32x2 wv[16];
; #pragma unroll
;       for (int rr = 0; rr < 16; ++rr) { if (isq) wv[rr] = *(const u32x2*)(rp + (size_t)(r0 + rr) * 512); else { wv[rr].x = *(const unsigned*)(rp + (size_t)(r0 + rr) * 512); wv[rr].y = 0u; } }
; #pragma unroll
;       for (int rr = 0; rr < 16; ++rr) {
;         const float a = bf2f(wv[rr].x & 0xffff), b = bf2f(wv[rr].x >> 16), c = bf2f(wv[rr].y & 0xffff), d = bf2f(wv[rr].y >> 16);
;         const float ss = wave_sum(a * a + b * b + c * c + d * d);
;         if (lane == 0) rsb[wid * 32 + r0 + rr] = rsqrtf(ss * (isq ? 1.0f / 256.0f : 1.0f / 128.0f) + 1e-6f);
;       }
	v_fmaak_f32 v32, v0, v32, 0x358637bd
	v_mul_f32_e32 v33, 0x4b800000, v32
	v_cmp_gt_f32_e32 vcc, s46, v32
	s_nop 1
	v_cndmask_b32_e32 v32, v32, v33, vcc
	v_rsq_f32_e32 v32, v32
	s_nop 0
	v_mul_f32_e32 v33, 0x45800000, v32
	v_cndmask_b32_e32 v32, v32, v33, vcc
	ds_write_b32 v36, v32
	v_fmaak_f32 v34, v0, v34, 0x358637bd
	v_mul_f32_e32 v35, 0x4b800000, v34
	v_cmp_gt_f32_e32 vcc, s46, v34
	s_nop 1
	v_cndmask_b32_e32 v34, v34, v35, vcc
	v_rsq_f32_e32 v34, v34
	s_nop 0
	v_mul_f32_e32 v35, 0x45800000, v34
	v_cndmask_b32_e32 v34, v34, v35, vcc
	ds_write_b32 v36, v34 offset:4
	v_fmaak_f32 v30, v0, v30, 0x358637bd
	v_mul_f32_e32 v31, 0x4b800000, v30
	v_cmp_gt_f32_e32 vcc, s46, v30
	s_nop 1
	v_cndmask_b32_e32 v30, v30, v31, vcc
	v_rsq_f32_e32 v30, v30
	s_nop 0
	v_mul_f32_e32 v31, 0x45800000, v30
	v_cndmask_b32_e32 v30, v30, v31, vcc
	ds_write_b32 v36, v30 offset:8
	v_fmaak_f32 v28, v0, v28, 0x358637bd
	v_mul_f32_e32 v29, 0x4b800000, v28
	v_cmp_gt_f32_e32 vcc, s46, v28
	s_nop 1
	v_cndmask_b32_e32 v28, v28, v29, vcc
	v_rsq_f32_e32 v28, v28
	s_nop 0
	v_mul_f32_e32 v29, 0x45800000, v28
	v_cndmask_b32_e32 v28, v28, v29, vcc
	ds_write_b32 v36, v28 offset:12
	v_fmaak_f32 v26, v0, v26, 0x358637bd
	v_mul_f32_e32 v27, 0x4b800000, v26
	v_cmp_gt_f32_e32 vcc, s46, v26
	s_nop 1
	v_cndmask_b32_e32 v26, v26, v27, vcc
	v_rsq_f32_e32 v26, v26
	s_nop 0
	v_mul_f32_e32 v27, 0x45800000, v26
	v_cndmask_b32_e32 v26, v26, v27, vcc
	ds_write_b32 v36, v26 offset:16
	v_fmaak_f32 v24, v0, v24, 0x358637bd
	v_mul_f32_e32 v25, 0x4b800000, v24
	v_cmp_gt_f32_e32 vcc, s46, v24
	s_nop 1
	v_cndmask_b32_e32 v24, v24, v25, vcc
	v_rsq_f32_e32 v24, v24
	s_nop 0
	v_mul_f32_e32 v25, 0x45800000, v24
	v_cndmask_b32_e32 v24, v24, v25, vcc
	ds_write_b32 v36, v24 offset:20
	v_fmaak_f32 v22, v0, v22, 0x358637bd
	v_mul_f32_e32 v23, 0x4b800000, v22
	v_cmp_gt_f32_e32 vcc, s46, v22
	s_nop 1
	v_cndmask_b32_e32 v22, v22, v23, vcc
	v_rsq_f32_e32 v22, v22
	s_nop 0
	v_mul_f32_e32 v23, 0x45800000, v22
	v_cndmask_b32_e32 v22, v22, v23, vcc
	ds_write_b32 v36, v22 offset:24
	v_fmaak_f32 v20, v0, v20, 0x358637bd
	v_mul_f32_e32 v21, 0x4b800000, v20
	v_cmp_gt_f32_e32 vcc, s46, v20
	s_nop 1
	v_cndmask_b32_e32 v20, v20, v21, vcc
	v_rsq_f32_e32 v20, v20
	s_nop 0
	v_mul_f32_e32 v21, 0x45800000, v20
	v_cndmask_b32_e32 v20, v20, v21, vcc
	ds_write_b32 v36, v20 offset:28
	v_fmaak_f32 v18, v0, v18, 0x358637bd
	v_mul_f32_e32 v19, 0x4b800000, v18
	v_cmp_gt_f32_e32 vcc, s46, v18
	s_nop 1
	v_cndmask_b32_e32 v18, v18, v19, vcc
	v_rsq_f32_e32 v18, v18
	s_nop 0
	v_mul_f32_e32 v19, 0x45800000, v18
	v_cndmask_b32_e32 v18, v18, v19, vcc
	ds_write_b32 v36, v18 offset:32
	v_fmaak_f32 v16, v0, v16, 0x358637bd
	v_mul_f32_e32 v17, 0x4b800000, v16
	v_cmp_gt_f32_e32 vcc, s46, v16
	s_nop 1
	v_cndmask_b32_e32 v16, v16, v17, vcc
	v_rsq_f32_e32 v16, v16
	s_nop 0
	v_mul_f32_e32 v17, 0x45800000, v16
	v_cndmask_b32_e32 v16, v16, v17, vcc
	ds_write_b32 v36, v16 offset:36
	v_fmaak_f32 v14, v0, v14, 0x358637bd
	v_mul_f32_e32 v15, 0x4b800000, v14
	v_cmp_gt_f32_e32 vcc, s46, v14
	s_nop 1
	v_cndmask_b32_e32 v14, v14, v15, vcc
	v_rsq_f32_e32 v14, v14
	s_nop 0
	v_mul_f32_e32 v15, 0x45800000, v14
	v_cndmask_b32_e32 v14, v14, v15, vcc
	ds_write_b32 v36, v14 offset:40
	v_fmaak_f32 v12, v0, v12, 0x358637bd
	v_mul_f32_e32 v13, 0x4b800000, v12
	v_cmp_gt_f32_e32 vcc, s46, v12
	s_nop 1
	v_cndmask_b32_e32 v12, v12, v13, vcc
	v_rsq_f32_e32 v12, v12
	s_nop 0
	v_mul_f32_e32 v13, 0x45800000, v12
	v_cndmask_b32_e32 v12, v12, v13, vcc
	ds_write_b32 v36, v12 offset:44
	v_fmaak_f32 v10, v0, v10, 0x358637bd
	v_mul_f32_e32 v11, 0x4b800000, v10
	v_cmp_gt_f32_e32 vcc, s46, v10
	s_nop 1
	v_cndmask_b32_e32 v10, v10, v11, vcc
	v_rsq_f32_e32 v10, v10
	s_nop 0
	v_mul_f32_e32 v11, 0x45800000, v10
	v_cndmask_b32_e32 v10, v10, v11, vcc
	ds_write_b32 v36, v10 offset:48
	v_fmaak_f32 v8, v0, v8, 0x358637bd
	v_mul_f32_e32 v9, 0x4b800000, v8
	v_cmp_gt_f32_e32 vcc, s46, v8
	s_nop 1
	v_cndmask_b32_e32 v8, v8, v9, vcc
	v_rsq_f32_e32 v8, v8
	s_nop 0
	v_mul_f32_e32 v9, 0x45800000, v8
	v_cndmask_b32_e32 v8, v8, v9, vcc
	ds_write_b32 v36, v8 offset:52
	v_fmaak_f32 v6, v0, v6, 0x358637bd
	v_mul_f32_e32 v7, 0x4b800000, v6
	v_cmp_gt_f32_e32 vcc, s46, v6
	s_nop 1
	v_cndmask_b32_e32 v6, v6, v7, vcc
	v_rsq_f32_e32 v6, v6
	s_nop 0
	v_mul_f32_e32 v7, 0x45800000, v6
	v_cndmask_b32_e32 v6, v6, v7, vcc
	ds_write_b32 v36, v6 offset:56
	v_fmaak_f32 v4, v0, v4, 0x358637bd
	v_mul_f32_e32 v5, 0x4b800000, v4
	v_cmp_gt_f32_e32 vcc, s46, v4
	s_nop 1
	v_cndmask_b32_e32 v4, v4, v5, vcc
	v_rsq_f32_e32 v4, v4
	s_nop 0
	v_mul_f32_e32 v5, 0x45800000, v4
	v_cndmask_b32_e32 v4, v4, v5, vcc
	ds_write_b32 v36, v4 offset:60
	s_branch .LBB0_843
